# norm+modulate phases: the 12 gain/shift/scale loads of a row issued together during the row reduction instead of a per-quarter load-wait ladder
# speedup vs baseline: 1.0142x; 1.0127x over previous
; __device__ __forceinline__ unsigned cvt_pk_bf16(float lo, float hi) { const f32x2_ v = {lo, hi}; return __builtin_bit_cast(unsigned, __builtin_convertvector(v, bf16x2_)); }
; __device__ void norm_mod_phase(const float* srcL, const float* srcC, float* cpyL, float* cpyC, const float* g, const float* mod, bf16_t* TN, int nrows, const float* pb, int nsl) {
;     ...
; #pragma unroll
;         for (int j = 0; j < 4; ++j) ss += v[j][0] * v[j][0] + v[j][1] * v[j][1] + v[j][2] * v[j][2] + v[j][3] * v[j][3];
;         if (cpyL) { float* cp = lat ? cpyL + (size_t)row * 1024 : cpyC + (size_t)(row - RL) * 1024;
; #pragma unroll
;             for (int j = 0; j < 4; ++j) *(f32x4*)(cp + 256 * j + 4 * lane) = v[j]; }
;         ss = wave_sum(ss);
;         const float rstd = rsqrtf(ss * (1.0f / 1024.0f) + NEPS);
; #pragma unroll
;         for (int j = 0; j < 4; ++j) {
;             const int col = 256 * j + 4 * lane;
;             const f32x4 gg = *(const f32x4*)(g + col), sh = *(const f32x4*)(mp + col), sc = *(const f32x4*)(mp + 1024 + col);
;             float o[4];
; #pragma unroll
;             for (int e = 0; e < 4; ++e) o[e] = (v[j][e] * rstd * gg[e]) * (1.0f + sc[e]) + sh[e];
;             u32x2 w; w.x = cvt_pk_bf16(o[0], o[1]); w.y = cvt_pk_bf16(o[2], o[3]);
;             *(u32x2*)(TN + (size_t)row * 1024 + col) = w;
;         }
.LBB0_28:
	s_or_b64 exec, exec, s[2:3]
	v_min_i32_e32 v27, 0x8000, v18
	v_ashrrev_i32_e32 v27, 13, v27
	v_mul_i32_i24_e32 v36, 0x2400, v27
	v_ashrrev_i32_e32 v37, 31, v36
	s_waitcnt vmcnt(2)
	v_mov_b32_e32 v38, v11
	v_mov_b32_e32 v39, v15
	v_lshl_add_u64 v[40:41], v[36:37], 2, s[6:7]
	v_mov_b32_e32 v36, v10
	v_mov_b32_e32 v37, v14
	v_pk_mul_f32 v[38:39], v[38:39], v[38:39]
	s_waitcnt vmcnt(0)
	v_mov_b32_e32 v46, v3
	v_pk_fma_f32 v[36:37], v[36:37], v[36:37], v[38:39]
	v_mov_b32_e32 v38, v12
	v_mov_b32_e32 v39, v16
	v_pk_fma_f32 v[36:37], v[38:39], v[38:39], v[36:37]
	v_mov_b32_e32 v38, v13
	v_mov_b32_e32 v39, v17
	v_mov_b32_e32 v47, v7
	v_pk_fma_f32 v[36:37], v[38:39], v[38:39], v[36:37]
	v_mov_b32_e32 v38, v2
	v_mov_b32_e32 v39, v6
	v_pk_mul_f32 v[46:47], v[46:47], v[46:47]
	v_mov_b32_e32 v31, v220
	v_pk_fma_f32 v[38:39], v[38:39], v[38:39], v[46:47]
	v_mov_b32_e32 v46, v4
	v_mov_b32_e32 v47, v8
	v_pk_fma_f32 v[38:39], v[46:47], v[46:47], v[38:39]
	v_mov_b32_e32 v46, v5
	v_mov_b32_e32 v47, v9
	v_pk_fma_f32 v[38:39], v[46:47], v[46:47], v[38:39]
	v_add_f32_e32 v27, v36, v37
	v_add_f32_e32 v27, v39, v27
	v_lshlrev_b32_e32 v31, 2, v31
	v_add_f32_e32 v27, v38, v27
	v_xor_b32_e32 v31, 0x80, v31
	ds_bpermute_b32 v31, v31, v27
	s_mov_b64 s[2:3], 0x1000
	v_lshl_add_u64 v[38:39], v[40:41], 0, s[2:3]
	v_mov_b32_e32 v96, v26
	v_mov_b32_e32 v97, v0
	v_lshl_add_u64 v[98:99], v[40:41], 0, v[96:97]
	v_lshl_add_u64 v[100:101], v[38:39], 0, v[96:97]
	global_load_dwordx4 v[46:49], v[22:23], off
	global_load_dwordx4 v[60:63], v[22:23], off offset:1024
	global_load_dwordx4 v[64:67], v[22:23], off offset:2048
	global_load_dwordx4 v[68:71], v[22:23], off offset:3072
	global_load_dwordx4 v[50:53], v[98:99], off
	global_load_dwordx4 v[72:75], v[98:99], off offset:1024
	global_load_dwordx4 v[76:79], v[98:99], off offset:2048
	global_load_dwordx4 v[80:83], v[98:99], off offset:3072
	global_load_dwordx4 v[54:57], v[100:101], off
	global_load_dwordx4 v[84:87], v[100:101], off offset:1024
	global_load_dwordx4 v[88:91], v[100:101], off offset:2048
	global_load_dwordx4 v[92:95], v[100:101], off offset:3072
	v_mov_b32_e32 v33, v0
	v_mov_b32_e32 v35, v0
	s_waitcnt lgkmcnt(0)
	v_add_f32_e32 v27, v27, v31
	v_mov_b32_e32 v31, v220
	v_lshl_add_u64 v[18:19], v[18:19], 0, s[8:9]
	v_lshlrev_b32_e32 v31, 2, v31
	v_xor_b32_e32 v31, 64, v31
	ds_bpermute_b32 v31, v31, v27
	s_waitcnt lgkmcnt(0)
	v_add_f32_e32 v27, v27, v31
	v_mov_b32_e32 v31, v220
	s_nop 0
	v_lshlrev_b32_e32 v31, 2, v31
	v_xor_b32_e32 v31, 32, v31
	ds_bpermute_b32 v31, v31, v27
	s_waitcnt lgkmcnt(0)
	v_add_f32_e32 v27, v27, v31
	v_mov_b32_e32 v31, v220
	s_nop 0
	v_lshlrev_b32_e32 v31, 2, v31
	v_xor_b32_e32 v31, 16, v31
	ds_bpermute_b32 v31, v31, v27
	s_waitcnt lgkmcnt(0)
	v_add_f32_e32 v27, v27, v31
	v_mov_b32_e32 v31, v220
	s_nop 0
	v_lshlrev_b32_e32 v31, 2, v31
	v_xor_b32_e32 v31, 8, v31
	ds_bpermute_b32 v31, v31, v27
	s_waitcnt lgkmcnt(0)
	v_add_f32_e32 v27, v27, v31
	v_mov_b32_e32 v31, v220
	v_lshlrev_b32_e32 v31, 2, v31
	v_xor_b32_e32 v31, 4, v31
	ds_bpermute_b32 v31, v31, v27
	s_waitcnt lgkmcnt(0)
	v_add_f32_e32 v27, v27, v31
	v_fmamk_f32 v27, v27, 0x3a800000, v188
	v_cmp_gt_f32_e32 vcc, s44, v27
	v_mul_f32_e32 v31, 0x4b800000, v27
	s_nop 0
	v_cndmask_b32_e32 v27, v27, v31, vcc
	v_rsq_f32_e32 v27, v27
	s_nop 0
	v_mul_f32_e32 v31, 0x45800000, v27
	v_cndmask_b32_e32 v36, v27, v31, vcc
	v_mov_b32_e32 v27, v0
	v_pk_mul_f32 v[14:15], v[14:15], v[36:37] op_sel_hi:[1,0]
	v_pk_mul_f32 v[16:17], v[16:17], v[36:37] op_sel_hi:[1,0]
	v_mov_b32_e32 v31, v0
	v_pk_mul_f32 v[10:11], v[10:11], v[36:37] op_sel_hi:[1,0]
	v_pk_mul_f32 v[12:13], v[12:13], v[36:37] op_sel_hi:[1,0]
	v_pk_mul_f32 v[6:7], v[6:7], v[36:37] op_sel_hi:[1,0]
	v_pk_mul_f32 v[8:9], v[8:9], v[36:37] op_sel_hi:[1,0]
	v_pk_mul_f32 v[2:3], v[2:3], v[36:37] op_sel_hi:[1,0]
	v_pk_mul_f32 v[4:5], v[4:5], v[36:37] op_sel_hi:[1,0]
	v_cmp_le_i32_e32 vcc, s0, v18
	s_or_b64 s[12:13], vcc, s[12:13]
	s_waitcnt vmcnt(0)
	v_pk_mul_f32 v[14:15], v[46:47], v[14:15]
	v_pk_mul_f32 v[16:17], v[48:49], v[16:17]
	v_pk_add_f32 v[46:47], v[54:55], 1.0 op_sel_hi:[1,0]
	s_nop 0
	v_pk_fma_f32 v[14:15], v[46:47], v[14:15], v[50:51]
	v_pk_add_f32 v[46:47], v[56:57], 1.0 op_sel_hi:[1,0]
	v_cvt_pk_bf16_f32 v14, v14, v15
	v_pk_fma_f32 v[16:17], v[46:47], v[16:17], v[52:53]
	s_nop 0
	v_cvt_pk_bf16_f32 v15, v16, v17
	global_store_dwordx2 v[24:25], v[14:15], off
	v_pk_mul_f32 v[10:11], v[60:61], v[10:11]
	v_pk_mul_f32 v[12:13], v[62:63], v[12:13]
	v_pk_add_f32 v[14:15], v[84:85], 1.0 op_sel_hi:[1,0]
	s_nop 0
	v_pk_fma_f32 v[10:11], v[14:15], v[10:11], v[72:73]
	v_pk_add_f32 v[14:15], v[86:87], 1.0 op_sel_hi:[1,0]
	v_cvt_pk_bf16_f32 v10, v10, v11
	v_pk_fma_f32 v[12:13], v[14:15], v[12:13], v[74:75]
	s_nop 0
	v_cvt_pk_bf16_f32 v11, v12, v13
	global_store_dwordx2 v[24:25], v[10:11], off offset:512
	v_pk_mul_f32 v[6:7], v[64:65], v[6:7]
	v_pk_mul_f32 v[8:9], v[66:67], v[8:9]
	v_pk_add_f32 v[10:11], v[88:89], 1.0 op_sel_hi:[1,0]
	s_nop 0
	v_pk_fma_f32 v[6:7], v[6:7], v[10:11], v[76:77]
	v_pk_add_f32 v[10:11], v[90:91], 1.0 op_sel_hi:[1,0]
	v_cvt_pk_bf16_f32 v6, v6, v7
	v_pk_fma_f32 v[8:9], v[8:9], v[10:11], v[78:79]
	s_nop 0
	v_cvt_pk_bf16_f32 v7, v8, v9
	global_store_dwordx2 v[24:25], v[6:7], off offset:1024
	v_pk_mul_f32 v[2:3], v[2:3], v[68:69]
	v_pk_mul_f32 v[4:5], v[4:5], v[70:71]
	v_pk_add_f32 v[6:7], v[92:93], 1.0 op_sel_hi:[1,0]
	s_nop 0
	v_pk_fma_f32 v[2:3], v[2:3], v[6:7], v[80:81]
	v_pk_add_f32 v[6:7], v[94:95], 1.0 op_sel_hi:[1,0]
	v_cvt_pk_bf16_f32 v2, v2, v3
	v_pk_fma_f32 v[4:5], v[4:5], v[6:7], v[82:83]
	s_nop 0
	v_cvt_pk_bf16_f32 v3, v4, v5
	global_store_dwordx2 v[24:25], v[2:3], off offset:1536
	v_lshl_add_u64 v[24:25], v[24:25], 0, s[10:11]
	s_andn2_b64 exec, exec, s[12:13]
	s_cbranch_execz .LBB0_31

; __device__ __forceinline__ unsigned cvt_pk_bf16(float lo, float hi) { const f32x2_ v = {lo, hi}; return __builtin_bit_cast(unsigned, __builtin_convertvector(v, bf16x2_)); }
; __device__ void norm_mod_phase(const float* srcL, const float* srcC, float* cpyL, float* cpyC, const float* g, const float* mod, bf16_t* TN, int nrows, const float* pb, int nsl) {
;     ...
; #pragma unroll
;         for (int j = 0; j < 4; ++j) ss += v[j][0] * v[j][0] + v[j][1] * v[j][1] + v[j][2] * v[j][2] + v[j][3] * v[j][3];
;         if (cpyL) { float* cp = lat ? cpyL + (size_t)row * 1024 : cpyC + (size_t)(row - RL) * 1024;
; #pragma unroll
;             for (int j = 0; j < 4; ++j) *(f32x4*)(cp + 256 * j + 4 * lane) = v[j]; }
;         ss = wave_sum(ss);
;         const float rstd = rsqrtf(ss * (1.0f / 1024.0f) + NEPS);
; #pragma unroll
;         for (int j = 0; j < 4; ++j) {
;             const int col = 256 * j + 4 * lane;
;             const f32x4 gg = *(const f32x4*)(g + col), sh = *(const f32x4*)(mp + col), sc = *(const f32x4*)(mp + 1024 + col);
;             float o[4];
; #pragma unroll
;             for (int e = 0; e < 4; ++e) o[e] = (v[j][e] * rstd * gg[e]) * (1.0f + sc[e]) + sh[e];
;             u32x2 w; w.x = cvt_pk_bf16(o[0], o[1]); w.y = cvt_pk_bf16(o[2], o[3]);
;             *(u32x2*)(TN + (size_t)row * 1024 + col) = w;
;         }
.LBB0_532:
	s_or_b64 exec, exec, s[2:3]
	v_min_i32_e32 v1, 0x8000, v18
	v_ashrrev_i32_e32 v1, 13, v1
	v_mul_i32_i24_e32 v34, 0x2400, v1
	v_ashrrev_i32_e32 v35, 31, v34
	s_waitcnt vmcnt(2)
	v_mov_b32_e32 v36, v7
	v_mov_b32_e32 v37, v11
	v_lshl_add_u64 v[38:39], v[34:35], 2, s[8:9]
	v_mov_b32_e32 v34, v6
	v_mov_b32_e32 v35, v10
	v_pk_mul_f32 v[36:37], v[36:37], v[36:37]
	s_waitcnt vmcnt(0)
	v_mov_b32_e32 v40, v15
	v_pk_fma_f32 v[34:35], v[34:35], v[34:35], v[36:37]
	v_mov_b32_e32 v36, v8
	v_mov_b32_e32 v37, v12
	v_pk_fma_f32 v[34:35], v[36:37], v[36:37], v[34:35]
	v_mov_b32_e32 v36, v9
	v_mov_b32_e32 v37, v13
	v_mov_b32_e32 v41, v3
	v_pk_fma_f32 v[34:35], v[36:37], v[36:37], v[34:35]
	v_mov_b32_e32 v36, v14
	v_mov_b32_e32 v37, v2
	v_pk_mul_f32 v[40:41], v[40:41], v[40:41]
	v_mov_b32_e32 v29, v220
	v_pk_fma_f32 v[36:37], v[36:37], v[36:37], v[40:41]
	v_mov_b32_e32 v40, v16
	v_mov_b32_e32 v41, v4
	v_pk_fma_f32 v[36:37], v[40:41], v[40:41], v[36:37]
	v_mov_b32_e32 v40, v17
	v_mov_b32_e32 v41, v5
	v_pk_fma_f32 v[36:37], v[40:41], v[40:41], v[36:37]
	v_add_f32_e32 v1, v34, v35
	v_add_f32_e32 v1, v37, v1
	v_lshlrev_b32_e32 v29, 2, v29
	v_add_f32_e32 v1, v36, v1
	v_xor_b32_e32 v29, 0x80, v29
	ds_bpermute_b32 v29, v29, v1
	s_mov_b64 s[2:3], 0x1000
	v_lshl_add_u64 v[36:37], v[38:39], 0, s[2:3]
	v_lshl_add_u64 v[38:39], v[38:39], 0, v[26:27]
	v_lshl_add_u64 v[48:49], v[36:37], 0, v[26:27]
	s_waitcnt lgkmcnt(0)
	v_add_f32_e32 v1, v1, v29
	v_mov_b32_e32 v29, v220
	v_mov_b32_e32 v31, v0
	v_lshlrev_b32_e32 v29, 2, v29
	v_xor_b32_e32 v29, 64, v29
	ds_bpermute_b32 v29, v29, v1
	v_mov_b32_e32 v33, v0
	v_lshl_add_u64 v[18:19], v[18:19], 0, s[10:11]
	s_waitcnt lgkmcnt(0)
	v_add_f32_e32 v1, v1, v29
	v_mov_b32_e32 v29, v220
	s_nop 0
	v_lshlrev_b32_e32 v29, 2, v29
	v_xor_b32_e32 v29, 32, v29
	ds_bpermute_b32 v29, v29, v1
	s_waitcnt lgkmcnt(0)
	v_add_f32_e32 v1, v1, v29
	v_mov_b32_e32 v29, v220
	s_nop 0
	v_lshlrev_b32_e32 v29, 2, v29
	v_xor_b32_e32 v29, 16, v29
	ds_bpermute_b32 v29, v29, v1
	s_waitcnt lgkmcnt(0)
	v_add_f32_e32 v1, v1, v29
	v_mov_b32_e32 v29, v220
	s_nop 0
	v_lshlrev_b32_e32 v29, 2, v29
	v_xor_b32_e32 v29, 8, v29
	ds_bpermute_b32 v29, v29, v1
	s_waitcnt lgkmcnt(0)
	v_add_f32_e32 v1, v1, v29
	v_mov_b32_e32 v29, v220
	global_load_dwordx4 v[40:43], v[22:23], off
	global_load_dwordx4 v[44:47], v[38:39], off
	global_load_dwordx4 v[60:63], v[22:23], off offset:1024
	global_load_dwordx4 v[64:67], v[22:23], off offset:2048
	global_load_dwordx4 v[68:71], v[22:23], off offset:3072
	global_load_dwordx4 v[72:75], v[38:39], off offset:1024
	global_load_dwordx4 v[76:79], v[38:39], off offset:2048
	global_load_dwordx4 v[80:83], v[38:39], off offset:3072
	global_load_dwordx4 v[84:87], v[48:49], off offset:1024
	global_load_dwordx4 v[88:91], v[48:49], off offset:2048
	global_load_dwordx4 v[92:95], v[48:49], off offset:3072
	v_lshlrev_b32_e32 v29, 2, v29
	global_load_dwordx4 v[48:51], v[48:49], off
	v_xor_b32_e32 v29, 4, v29
	ds_bpermute_b32 v29, v29, v1
	s_waitcnt lgkmcnt(0)
	v_add_f32_e32 v1, v1, v29
	v_fmamk_f32 v1, v1, 0x3a800000, v188
	v_cmp_gt_f32_e32 vcc, s44, v1
	v_mul_f32_e32 v29, 0x4b800000, v1
	s_nop 0
	v_cndmask_b32_e32 v1, v1, v29, vcc
	v_rsq_f32_e32 v1, v1
	s_nop 0
	v_mul_f32_e32 v29, 0x45800000, v1
	v_cndmask_b32_e32 v34, v1, v29, vcc
	v_pk_mul_f32 v[10:11], v[10:11], v[34:35] op_sel_hi:[1,0]
	v_pk_mul_f32 v[12:13], v[12:13], v[34:35] op_sel_hi:[1,0]
	v_mov_b32_e32 v29, v0
	v_pk_mul_f32 v[6:7], v[6:7], v[34:35] op_sel_hi:[1,0]
	v_pk_mul_f32 v[8:9], v[8:9], v[34:35] op_sel_hi:[1,0]
	v_pk_mul_f32 v[2:3], v[2:3], v[34:35] op_sel_hi:[1,0]
	v_pk_mul_f32 v[4:5], v[4:5], v[34:35] op_sel_hi:[1,0]
	v_pk_mul_f32 v[14:15], v[14:15], v[34:35] op_sel_hi:[1,0]
	v_cmp_lt_i32_e32 vcc, s45, v18
	s_or_b64 s[14:15], vcc, s[14:15]
	s_waitcnt vmcnt(0)
	v_pk_mul_f32 v[10:11], v[40:41], v[10:11]
	v_pk_mul_f32 v[12:13], v[42:43], v[12:13]
	v_pk_add_f32 v[40:41], v[48:49], 1.0 op_sel_hi:[1,0]
	s_nop 0
	v_pk_fma_f32 v[10:11], v[40:41], v[10:11], v[44:45]
	v_pk_add_f32 v[40:41], v[50:51], 1.0 op_sel_hi:[1,0]
	v_cvt_pk_bf16_f32 v10, v10, v11
	v_pk_fma_f32 v[12:13], v[40:41], v[12:13], v[46:47]
	s_nop 0
	v_cvt_pk_bf16_f32 v11, v12, v13
	global_store_dwordx2 v[24:25], v[10:11], off
	v_pk_mul_f32 v[6:7], v[60:61], v[6:7]
	v_pk_mul_f32 v[8:9], v[62:63], v[8:9]
	v_pk_add_f32 v[10:11], v[84:85], 1.0 op_sel_hi:[1,0]
	s_nop 0
	v_pk_fma_f32 v[6:7], v[10:11], v[6:7], v[72:73]
	v_pk_add_f32 v[10:11], v[86:87], 1.0 op_sel_hi:[1,0]
	v_cvt_pk_bf16_f32 v6, v6, v7
	v_pk_fma_f32 v[8:9], v[10:11], v[8:9], v[74:75]
	s_nop 0
	v_cvt_pk_bf16_f32 v7, v8, v9
	global_store_dwordx2 v[24:25], v[6:7], off offset:512
	v_pk_mul_f32 v[2:3], v[64:65], v[2:3]
	v_pk_mul_f32 v[4:5], v[66:67], v[4:5]
	v_pk_add_f32 v[6:7], v[88:89], 1.0 op_sel_hi:[1,0]
	s_nop 0
	v_pk_fma_f32 v[2:3], v[2:3], v[6:7], v[76:77]
	v_pk_add_f32 v[6:7], v[90:91], 1.0 op_sel_hi:[1,0]
	v_cvt_pk_bf16_f32 v2, v2, v3
	v_pk_fma_f32 v[4:5], v[4:5], v[6:7], v[78:79]
	s_nop 0
	v_cvt_pk_bf16_f32 v3, v4, v5
	global_store_dwordx2 v[24:25], v[2:3], off offset:1024
	v_pk_mul_f32 v[2:3], v[14:15], v[68:69]
	v_pk_add_f32 v[10:11], v[92:93], 1.0 op_sel_hi:[1,0]
	s_nop 0
	v_pk_fma_f32 v[2:3], v[2:3], v[10:11], v[80:81]
	v_pk_mul_f32 v[6:7], v[16:17], v[34:35] op_sel_hi:[1,0]
	v_cvt_pk_bf16_f32 v2, v2, v3
	v_pk_mul_f32 v[4:5], v[6:7], v[70:71]
	v_pk_add_f32 v[6:7], v[94:95], 1.0 op_sel_hi:[1,0]
	s_nop 0
	v_pk_fma_f32 v[4:5], v[4:5], v[6:7], v[82:83]
	s_nop 0
	v_cvt_pk_bf16_f32 v3, v4, v5
	global_store_dwordx2 v[24:25], v[2:3], off offset:1536
	v_lshl_add_u64 v[24:25], v[24:25], 0, s[12:13]
	s_andn2_b64 exec, exec, s[14:15]
	s_cbranch_execz .LBB0_535

; __device__ __forceinline__ unsigned cvt_pk_bf16(float lo, float hi) { const f32x2_ v = {lo, hi}; return __builtin_bit_cast(unsigned, __builtin_convertvector(v, bf16x2_)); }
; __device__ void norm_mod_phase(const float* srcL, const float* srcC, float* cpyL, float* cpyC, const float* g, const float* mod, bf16_t* TN, int nrows, const float* pb, int nsl) {
;     ...
; #pragma unroll
;         for (int j = 0; j < 4; ++j) ss += v[j][0] * v[j][0] + v[j][1] * v[j][1] + v[j][2] * v[j][2] + v[j][3] * v[j][3];
;         if (cpyL) { float* cp = lat ? cpyL + (size_t)row * 1024 : cpyC + (size_t)(row - RL) * 1024;
; #pragma unroll
;             for (int j = 0; j < 4; ++j) *(f32x4*)(cp + 256 * j + 4 * lane) = v[j]; }
;         ss = wave_sum(ss);
;         const float rstd = rsqrtf(ss * (1.0f / 1024.0f) + NEPS);
; #pragma unroll
;         for (int j = 0; j < 4; ++j) {
;             const int col = 256 * j + 4 * lane;
;             const f32x4 gg = *(const f32x4*)(g + col), sh = *(const f32x4*)(mp + col), sc = *(const f32x4*)(mp + 1024 + col);
;             float o[4];
; #pragma unroll
;             for (int e = 0; e < 4; ++e) o[e] = (v[j][e] * rstd * gg[e]) * (1.0f + sc[e]) + sh[e];
;             u32x2 w; w.x = cvt_pk_bf16(o[0], o[1]); w.y = cvt_pk_bf16(o[2], o[3]);
;             *(u32x2*)(TN + (size_t)row * 1024 + col) = w;
;         }
.LBB0_634:
	s_or_b64 exec, exec, s[2:3]
	v_min_i32_e32 v1, 0x8000, v18
	v_ashrrev_i32_e32 v1, 13, v1
	v_mul_i32_i24_e32 v34, 0x2400, v1
	v_ashrrev_i32_e32 v35, 31, v34
	v_lshl_add_u64 v[38:39], v[34:35], 2, s[10:11]
	s_waitcnt vmcnt(2)
	v_mov_b32_e32 v36, v7
	v_mov_b32_e32 v37, v11
	s_mov_b64 s[2:3], 0x1000
	v_mov_b32_e32 v34, v6
	v_mov_b32_e32 v35, v10
	v_pk_mul_f32 v[36:37], v[36:37], v[36:37]
	v_lshl_add_u64 v[50:51], v[38:39], 0, s[2:3]
	v_pk_fma_f32 v[34:35], v[34:35], v[34:35], v[36:37]
	v_mov_b32_e32 v36, v8
	v_mov_b32_e32 v37, v12
	v_mov_b32_e32 v1, v220
	v_mov_b32_e32 v29, v220
	v_mov_b32_e32 v31, v220
	v_mov_b32_e32 v33, v220
	v_mov_b32_e32 v56, v220
	v_mov_b32_e32 v57, v220
	v_lshl_add_u64 v[52:53], v[38:39], 0, v[26:27]
	v_lshl_add_u64 v[42:43], v[50:51], 0, v[26:27]
	v_pk_fma_f32 v[46:47], v[36:37], v[36:37], v[34:35]
	global_load_dwordx4 v[34:37], v[22:23], off
	global_load_dwordx4 v[38:41], v[52:53], off
	global_load_dwordx4 v[60:63], v[22:23], off offset:1024
	global_load_dwordx4 v[64:67], v[22:23], off offset:2048
	global_load_dwordx4 v[68:71], v[22:23], off offset:3072
	global_load_dwordx4 v[72:75], v[52:53], off offset:1024
	global_load_dwordx4 v[76:79], v[52:53], off offset:2048
	global_load_dwordx4 v[80:83], v[52:53], off offset:3072
	global_load_dwordx4 v[84:87], v[42:43], off offset:1024
	global_load_dwordx4 v[88:91], v[42:43], off offset:2048
	global_load_dwordx4 v[92:95], v[42:43], off offset:3072
	s_nop 0
	global_load_dwordx4 v[42:45], v[42:43], off
	v_mov_b32_e32 v48, v9
	v_mov_b32_e32 v49, v13
	s_waitcnt vmcnt(12)
	v_mov_b32_e32 v54, v15
	v_mov_b32_e32 v55, v3
	v_pk_fma_f32 v[46:47], v[48:49], v[48:49], v[46:47]
	v_mov_b32_e32 v48, v14
	v_mov_b32_e32 v49, v2
	v_pk_mul_f32 v[54:55], v[54:55], v[54:55]
	v_add_f32_e32 v27, v46, v47
	v_pk_fma_f32 v[48:49], v[48:49], v[48:49], v[54:55]
	v_mov_b32_e32 v54, v16
	v_mov_b32_e32 v55, v4
	v_pk_fma_f32 v[48:49], v[54:55], v[54:55], v[48:49]
	v_mov_b32_e32 v54, v17
	v_mov_b32_e32 v55, v5
	v_pk_fma_f32 v[48:49], v[54:55], v[54:55], v[48:49]
	v_lshlrev_b32_e32 v1, 2, v1
	v_add_f32_e32 v27, v49, v27
	v_add_f32_e32 v27, v48, v27
	v_xor_b32_e32 v1, 0x80, v1
	ds_bpermute_b32 v1, v1, v27
	v_lshl_add_u64 v[18:19], v[18:19], 0, s[12:13]
	s_waitcnt lgkmcnt(0)
	v_add_f32_e32 v1, v27, v1
	v_lshlrev_b32_e32 v27, 2, v29
	v_xor_b32_e32 v27, 64, v27
	ds_bpermute_b32 v27, v27, v1
	v_mov_b32_e32 v29, v0
	s_waitcnt lgkmcnt(0)
	v_add_f32_e32 v1, v1, v27
	v_lshlrev_b32_e32 v27, 2, v31
	v_xor_b32_e32 v27, 32, v27
	ds_bpermute_b32 v27, v27, v1
	v_mov_b32_e32 v31, v0
	s_waitcnt lgkmcnt(0)
	v_add_f32_e32 v1, v1, v27
	v_lshlrev_b32_e32 v27, 2, v33
	v_xor_b32_e32 v27, 16, v27
	ds_bpermute_b32 v27, v27, v1
	v_mov_b32_e32 v33, v0
	s_waitcnt lgkmcnt(0)
	v_add_f32_e32 v1, v1, v27
	v_lshlrev_b32_e32 v27, 2, v56
	v_xor_b32_e32 v27, 8, v27
	ds_bpermute_b32 v27, v27, v1
	s_waitcnt lgkmcnt(0)
	v_add_f32_e32 v1, v1, v27
	v_lshlrev_b32_e32 v27, 2, v57
	v_xor_b32_e32 v27, 4, v27
	ds_bpermute_b32 v27, v27, v1
	s_waitcnt lgkmcnt(0)
	v_add_f32_e32 v1, v1, v27
	v_fmamk_f32 v1, v1, 0x3a800000, v188
	v_mul_f32_e32 v27, 0x4b800000, v1
	v_cmp_gt_f32_e32 vcc, s44, v1
	s_nop 1
	v_cndmask_b32_e32 v1, v1, v27, vcc
	v_rsq_f32_e32 v1, v1
	s_nop 0
	v_mul_f32_e32 v27, 0x45800000, v1
	v_cndmask_b32_e32 v46, v1, v27, vcc
	v_pk_mul_f32 v[10:11], v[10:11], v[46:47] op_sel_hi:[1,0]
	v_pk_mul_f32 v[12:13], v[12:13], v[46:47] op_sel_hi:[1,0]
	s_waitcnt vmcnt(0)
	v_pk_mul_f32 v[10:11], v[34:35], v[10:11]
	v_pk_mul_f32 v[12:13], v[36:37], v[12:13]
	v_pk_add_f32 v[34:35], v[42:43], 1.0 op_sel_hi:[1,0]
	v_pk_add_f32 v[36:37], v[44:45], 1.0 op_sel_hi:[1,0]
	v_pk_fma_f32 v[10:11], v[34:35], v[10:11], v[38:39]
	v_pk_fma_f32 v[12:13], v[36:37], v[12:13], v[40:41]
	v_cvt_pk_bf16_f32 v10, v10, v11
	v_cvt_pk_bf16_f32 v11, v12, v13
	global_store_dwordx2 v[24:25], v[10:11], off
	v_pk_mul_f32 v[6:7], v[6:7], v[46:47] op_sel_hi:[1,0]
	v_pk_mul_f32 v[8:9], v[8:9], v[46:47] op_sel_hi:[1,0]
	v_pk_mul_f32 v[2:3], v[2:3], v[46:47] op_sel_hi:[1,0]
	v_pk_mul_f32 v[4:5], v[4:5], v[46:47] op_sel_hi:[1,0]
	v_pk_mul_f32 v[14:15], v[14:15], v[46:47] op_sel_hi:[1,0]
	v_pk_mul_f32 v[16:17], v[16:17], v[46:47] op_sel_hi:[1,0]
	v_cmp_lt_i32_e32 vcc, s45, v18
	s_or_b64 s[16:17], vcc, s[16:17]
	v_pk_mul_f32 v[6:7], v[60:61], v[6:7]
	v_pk_add_f32 v[10:11], v[84:85], 1.0 op_sel_hi:[1,0]
	v_pk_mul_f32 v[8:9], v[62:63], v[8:9]
	v_pk_add_f32 v[12:13], v[86:87], 1.0 op_sel_hi:[1,0]
	v_pk_fma_f32 v[6:7], v[10:11], v[6:7], v[72:73]
	v_pk_fma_f32 v[8:9], v[12:13], v[8:9], v[74:75]
	v_cvt_pk_bf16_f32 v6, v6, v7
	v_cvt_pk_bf16_f32 v7, v8, v9
	global_store_dwordx2 v[24:25], v[6:7], off offset:512
	v_pk_mul_f32 v[2:3], v[64:65], v[2:3]
	v_pk_add_f32 v[6:7], v[88:89], 1.0 op_sel_hi:[1,0]
	v_pk_mul_f32 v[4:5], v[66:67], v[4:5]
	v_pk_add_f32 v[8:9], v[90:91], 1.0 op_sel_hi:[1,0]
	v_pk_fma_f32 v[2:3], v[2:3], v[6:7], v[76:77]
	v_pk_fma_f32 v[4:5], v[4:5], v[8:9], v[78:79]
	v_cvt_pk_bf16_f32 v2, v2, v3
	v_cvt_pk_bf16_f32 v3, v4, v5
	global_store_dwordx2 v[24:25], v[2:3], off offset:1024
	v_pk_mul_f32 v[2:3], v[14:15], v[68:69]
	v_pk_add_f32 v[6:7], v[92:93], 1.0 op_sel_hi:[1,0]
	v_pk_mul_f32 v[4:5], v[16:17], v[70:71]
	v_pk_add_f32 v[8:9], v[94:95], 1.0 op_sel_hi:[1,0]
	v_pk_fma_f32 v[2:3], v[2:3], v[6:7], v[80:81]
	v_pk_fma_f32 v[4:5], v[4:5], v[8:9], v[82:83]
	v_cvt_pk_bf16_f32 v2, v2, v3
	v_cvt_pk_bf16_f32 v3, v4, v5
	global_store_dwordx2 v[24:25], v[2:3], off offset:1536
	v_lshl_add_u64 v[24:25], v[24:25], 0, s[14:15]
	s_andn2_b64 exec, exec, s[16:17]
	s_cbranch_execz .LBB0_637

; __device__ __forceinline__ unsigned cvt_pk_bf16(float lo, float hi) { const f32x2_ v = {lo, hi}; return __builtin_bit_cast(unsigned, __builtin_convertvector(v, bf16x2_)); }
; __device__ void norm_mod_phase(const float* srcL, const float* srcC, float* cpyL, float* cpyC, const float* g, const float* mod, bf16_t* TN, int nrows, const float* pb, int nsl) {
;     ...
; #pragma unroll
;         for (int j = 0; j < 4; ++j) ss += v[j][0] * v[j][0] + v[j][1] * v[j][1] + v[j][2] * v[j][2] + v[j][3] * v[j][3];
;         if (cpyL) { float* cp = lat ? cpyL + (size_t)row * 1024 : cpyC + (size_t)(row - RL) * 1024;
; #pragma unroll
;             for (int j = 0; j < 4; ++j) *(f32x4*)(cp + 256 * j + 4 * lane) = v[j]; }
;         ss = wave_sum(ss);
;         const float rstd = rsqrtf(ss * (1.0f / 1024.0f) + NEPS);
; #pragma unroll
;         for (int j = 0; j < 4; ++j) {
;             const int col = 256 * j + 4 * lane;
;             const f32x4 gg = *(const f32x4*)(g + col), sh = *(const f32x4*)(mp + col), sc = *(const f32x4*)(mp + 1024 + col);
;             float o[4];
; #pragma unroll
;             for (int e = 0; e < 4; ++e) o[e] = (v[j][e] * rstd * gg[e]) * (1.0f + sc[e]) + sh[e];
;             u32x2 w; w.x = cvt_pk_bf16(o[0], o[1]); w.y = cvt_pk_bf16(o[2], o[3]);
;             *(u32x2*)(TN + (size_t)row * 1024 + col) = w;
;         }
.LBB0_640:
	v_min_i32_e32 v1, 0x8000, v18
	v_ashrrev_i32_e32 v1, 13, v1
	v_mul_i32_i24_e32 v32, 0x2400, v1
	v_ashrrev_i32_e32 v33, 31, v32
	v_lshl_add_u64 v[40:41], v[32:33], 2, s[14:15]
	s_mov_b64 s[4:5], 0x1000
	v_lshl_add_u64 v[44:45], v[40:41], 0, s[4:5]
	v_mov_b32_e32 v1, v220
	v_mov_b32_e32 v27, v220
	v_mov_b32_e32 v29, v220
	v_mov_b32_e32 v31, v220
	v_mov_b32_e32 v48, v220
	v_mov_b32_e32 v49, v220
	v_lshl_add_u64 v[36:37], v[44:45], 0, v[24:25]
	global_load_dwordx4 v[32:35], v[20:21], off
	v_lshl_add_u64 v[46:47], v[40:41], 0, v[24:25]
	v_lshl_add_u64 v[98:99], v[44:45], 0, v[24:25]
	global_load_dwordx4 v[36:39], v[36:37], off
	s_waitcnt vmcnt(5)
	v_mul_f32_e32 v25, v15, v15
	global_load_dwordx4 v[40:43], v[46:47], off
	s_waitcnt vmcnt(5)
	v_mul_f32_e32 v50, v11, v11
	v_fmac_f32_e32 v25, v14, v14
	v_fmac_f32_e32 v50, v10, v10
	v_fmac_f32_e32 v25, v16, v16
	v_fmac_f32_e32 v50, v12, v12
	v_fmac_f32_e32 v25, v17, v17
	v_fmac_f32_e32 v50, v13, v13
	v_add_f32_e32 v25, v25, v50
	s_waitcnt vmcnt(4)
	v_mul_f32_e32 v50, v7, v7
	v_fmac_f32_e32 v50, v6, v6
	v_fmac_f32_e32 v50, v8, v8
	v_fmac_f32_e32 v50, v9, v9
	v_add_f32_e32 v25, v25, v50
	s_waitcnt vmcnt(3)
	global_load_dwordx4 v[60:63], v[20:21], off offset:1024
	global_load_dwordx4 v[64:67], v[20:21], off offset:2048
	global_load_dwordx4 v[68:71], v[20:21], off offset:3072
	global_load_dwordx4 v[72:75], v[46:47], off offset:1024
	global_load_dwordx4 v[76:79], v[46:47], off offset:2048
	global_load_dwordx4 v[80:83], v[46:47], off offset:3072
	global_load_dwordx4 v[84:87], v[98:99], off offset:1024
	global_load_dwordx4 v[88:91], v[98:99], off offset:2048
	global_load_dwordx4 v[92:95], v[98:99], off offset:3072
	v_mul_f32_e32 v50, v3, v3
	v_fmac_f32_e32 v50, v2, v2
	v_fmac_f32_e32 v50, v4, v4
	v_fmac_f32_e32 v50, v5, v5
	v_lshlrev_b32_e32 v1, 2, v1
	v_add_f32_e32 v25, v25, v50
	v_xor_b32_e32 v1, 0x80, v1
	ds_bpermute_b32 v1, v1, v25
	v_lshl_add_u64 v[18:19], v[18:19], 0, s[16:17]
	s_waitcnt lgkmcnt(0)
	v_add_f32_e32 v1, v25, v1
	v_lshlrev_b32_e32 v25, 2, v27
	v_xor_b32_e32 v25, 64, v25
	ds_bpermute_b32 v25, v25, v1
	v_lshlrev_b32_e32 v27, 2, v48
	v_xor_b32_e32 v27, 8, v27
	s_waitcnt lgkmcnt(0)
	v_add_f32_e32 v1, v1, v25
	v_lshlrev_b32_e32 v25, 2, v29
	v_xor_b32_e32 v25, 32, v25
	ds_bpermute_b32 v25, v25, v1
	v_mov_b32_e32 v29, v0
	s_waitcnt lgkmcnt(0)
	v_add_f32_e32 v1, v1, v25
	v_lshlrev_b32_e32 v25, 2, v31
	v_xor_b32_e32 v25, 16, v25
	ds_bpermute_b32 v25, v25, v1
	v_mov_b32_e32 v31, v0
	s_waitcnt lgkmcnt(0)
	v_add_f32_e32 v1, v1, v25
	ds_bpermute_b32 v25, v27, v1
	v_lshlrev_b32_e32 v27, 2, v49
	v_xor_b32_e32 v27, 4, v27
	s_waitcnt lgkmcnt(0)
	v_add_f32_e32 v1, v1, v25
	ds_bpermute_b32 v25, v27, v1
	v_mov_b32_e32 v27, v0
	v_lshl_add_u64 v[48:49], v[44:45], 0, v[26:27]
	s_waitcnt lgkmcnt(0)
	v_add_f32_e32 v1, v1, v25
	v_fmamk_f32 v1, v1, 0x3a800000, v188
	v_mul_f32_e32 v25, 0x4b800000, v1
	v_cmp_gt_f32_e32 vcc, s44, v1
	s_nop 1
	v_cndmask_b32_e32 v1, v1, v25, vcc
	v_rsq_f32_e32 v1, v1
	s_nop 0
	v_mul_f32_e32 v25, 0x45800000, v1
	v_cndmask_b32_e32 v50, v1, v25, vcc
	v_pk_mul_f32 v[14:15], v[14:15], v[50:51] op_sel_hi:[1,0]
	v_pk_mul_f32 v[16:17], v[16:17], v[50:51] op_sel_hi:[1,0]
	s_waitcnt vmcnt(0)
	v_pk_mul_f32 v[14:15], v[32:33], v[14:15]
	v_pk_mul_f32 v[16:17], v[34:35], v[16:17]
	v_pk_add_f32 v[32:33], v[36:37], 1.0 op_sel_hi:[1,0]
	v_pk_add_f32 v[34:35], v[38:39], 1.0 op_sel_hi:[1,0]
	v_pk_fma_f32 v[14:15], v[32:33], v[14:15], v[40:41]
	v_pk_fma_f32 v[16:17], v[34:35], v[16:17], v[42:43]
	v_cvt_pk_bf16_f32 v14, v14, v15
	v_cvt_pk_bf16_f32 v15, v16, v17
	global_store_dwordx2 v[22:23], v[14:15], off
	v_pk_mul_f32 v[10:11], v[10:11], v[50:51] op_sel_hi:[1,0]
	v_pk_mul_f32 v[12:13], v[12:13], v[50:51] op_sel_hi:[1,0]
	v_pk_mul_f32 v[6:7], v[6:7], v[50:51] op_sel_hi:[1,0]
	v_pk_mul_f32 v[8:9], v[8:9], v[50:51] op_sel_hi:[1,0]
	v_pk_mul_f32 v[2:3], v[2:3], v[50:51] op_sel_hi:[1,0]
	v_pk_mul_f32 v[4:5], v[4:5], v[50:51] op_sel_hi:[1,0]
	v_cmp_lt_i32_e32 vcc, s45, v18
	s_or_b64 s[18:19], vcc, s[18:19]
	v_pk_mul_f32 v[10:11], v[60:61], v[10:11]
	v_pk_add_f32 v[14:15], v[84:85], 1.0 op_sel_hi:[1,0]
	v_pk_mul_f32 v[12:13], v[62:63], v[12:13]
	v_pk_add_f32 v[16:17], v[86:87], 1.0 op_sel_hi:[1,0]
	v_pk_fma_f32 v[10:11], v[14:15], v[10:11], v[72:73]
	v_pk_fma_f32 v[12:13], v[16:17], v[12:13], v[74:75]
	v_cvt_pk_bf16_f32 v10, v10, v11
	v_cvt_pk_bf16_f32 v11, v12, v13
	global_store_dwordx2 v[22:23], v[10:11], off offset:512
	v_pk_mul_f32 v[6:7], v[64:65], v[6:7]
	v_pk_add_f32 v[10:11], v[88:89], 1.0 op_sel_hi:[1,0]
	v_pk_mul_f32 v[8:9], v[66:67], v[8:9]
	v_pk_add_f32 v[12:13], v[90:91], 1.0 op_sel_hi:[1,0]
	v_pk_fma_f32 v[6:7], v[6:7], v[10:11], v[76:77]
	v_pk_fma_f32 v[8:9], v[8:9], v[12:13], v[78:79]
	v_cvt_pk_bf16_f32 v6, v6, v7
	v_cvt_pk_bf16_f32 v7, v8, v9
	global_store_dwordx2 v[22:23], v[6:7], off offset:1024
	v_pk_mul_f32 v[2:3], v[2:3], v[68:69]
	v_pk_add_f32 v[6:7], v[92:93], 1.0 op_sel_hi:[1,0]
	v_pk_mul_f32 v[4:5], v[4:5], v[70:71]
	v_pk_add_f32 v[8:9], v[94:95], 1.0 op_sel_hi:[1,0]
	v_pk_fma_f32 v[2:3], v[2:3], v[6:7], v[80:81]
	v_pk_fma_f32 v[4:5], v[4:5], v[8:9], v[82:83]
	v_cvt_pk_bf16_f32 v2, v2, v3
	v_cvt_pk_bf16_f32 v3, v4, v5
	global_store_dwordx2 v[22:23], v[2:3], off offset:1536
	v_lshl_add_u64 v[22:23], v[22:23], 0, s[22:23]
	s_andn2_b64 exec, exec, s[18:19]
	s_cbranch_execz .LBB0_643
